# WKV block: commit conversions and hoisted transpose stage 1 placed in the DPP wait gaps
# baseline (speedup 1.0000x reference)
; #define LAS __attribute__((address_space(3)))
; #define LO2(v4) (__builtin_shufflevector(v4, v4, 0, 1))
; #define HI2(v4) (__builtin_shufflevector(v4, v4, 2, 3))
; __device__ __forceinline__ f32x2 fma2(f32x2 a, f32x2 b, f32x2 c) { return __builtin_elementwise_fma(a, b, c); }
; #define WKV_LOAD(d, s) do { const LAS float* p_ = bw + (s) * SCW; d.r = *(const LAS f32x4*)(p_); d.u = *(const LAS f32x4*)(p_ + 64); d.km = *(const LAS f32x4*)(p_ + 128); \
;                     d.kk = *(const LAS f32x4*)(p_ + 256); d.ka = *(const LAS f32x4*)(p_ + 320); d.v = bv[(s) * SCW]; } while (0)
; __device__ __forceinline__ void scan_phase(const Args& a, int e, LAS unsigned char* lds) {
;     ...
;                 const LAS float* bw = bufW + bi * TC * SCW + 4 * g; const LAS float* bv = bufW + bi * TC * SCW + 192 + vrow;
;     ...
;                 WkvIn in[3];
;                 WKV_LOAD(in[0], 0); WKV_LOAD(in[1], 1);
; #pragma unroll
;                 for (int s = 0; s < TC; ++s) {
;                     if (s + 2 < TC) WKV_LOAD(in[(s + 2) % 3], s + 2);
;                     __builtin_amdgcn_sched_barrier(0);
;                     const WkvIn& x = in[s % 3];
;                     const f32x2 vv = {x.v, x.v};
;                     const f32x2 s2 = fma2(P1, HI2(x.kk), P0 * LO2(x.kk));
;                     const f32x2 T0 = fma2(vv, LO2(x.km), fma2(-LO2(x.u), P0, P0)), T1 = fma2(vv, HI2(x.km), fma2(-HI2(x.u), P1, P1));
;                     const float sa = rowsum16(s2.x + s2.y);
;                     const f32x2 ns = {-sa, -sa};
;                     P0 = fma2(ns, LO2(x.ka), T0); P1 = fma2(ns, HI2(x.ka), T1);
;                     const f32x2 o2 = fma2(P1, HI2(x.r), P0 * LO2(x.r));
;                     op[s] = o2.x + o2.y;
;                 }
.LBB0_240:
	s_mul_i32 s15, s14, 0x6000
	v_or_b32_e32 v22, s15, v55
	v_lshl_or_b32 v51, v77, 2, s15
	ds_read_b128 v[122:125], v22 offset:0
	ds_read_b128 v[86:89], v22 offset:256
	ds_read_b128 v[102:105], v22 offset:512
	ds_read_b128 v[78:81], v22 offset:1024
	ds_read_b128 v[110:113], v22 offset:1280
	ds_read_b32 v136, v51 offset:768
	ds_read_b128 v[126:129], v22 offset:1536
	ds_read_b128 v[98:101], v22 offset:1792
	ds_read_b128 v[106:109], v22 offset:2048
	ds_read_b128 v[82:85], v22 offset:2560
	ds_read_b128 v[114:117], v22 offset:2816
	ds_read_b32 v138, v51 offset:2304
	s_cbranch_vccz .Lwkv_noload
	v_mov_b32_e32 v21, v1
	v_lshl_add_u64 v[6:7], v[0:1], 1, v[36:37]
	v_lshl_add_u64 v[10:11], v[20:21], 1, v[38:39]
	global_load_dwordx4 v[6:9], v[6:7], off
	v_mov_b32_e32 v19, v1
	global_load_dwordx4 v[10:13], v[10:11], off
	v_lshl_add_u64 v[2:3], v[18:19], 1, v[40:41]
	global_load_dwordx4 v[2:5], v[2:3], off
	v_add_u32_e32 v0, v0, v65
	v_add_u32_e32 v20, v20, v66
	v_add_u32_e32 v18, v18, v64
.Lwkv_noload:
	s_waitcnt lgkmcnt(6)
	v_pk_mul_f32 v[90:91], v[14:15], v[78:79]
	v_pk_fma_f32 v[94:95], v[86:87], v[14:15], v[14:15] neg_lo:[1,0,0] neg_hi:[1,0,0]
	v_pk_fma_f32 v[90:91], v[16:17], v[80:81], v[90:91]
	v_pk_fma_f32 v[134:135], v[88:89], v[16:17], v[16:17] neg_lo:[1,0,0] neg_hi:[1,0,0]
	v_add_f32_e32 v50, v90, v91
	v_pk_fma_f32 v[94:95], v[136:137], v[102:103], v[94:95] op_sel_hi:[0,1,1]
	v_pk_fma_f32 v[134:135], v[136:137], v[104:105], v[134:135] op_sel_hi:[0,1,1]
	v_add_f32_dpp v50, v50, v50 row_ror:8 row_mask:0xf bank_mask:0xf bound_ctrl:1
	ds_read_b128 v[130:133], v22 offset:3072
	ds_read_b128 v[86:89], v22 offset:3328
	v_add_f32_dpp v50, v50, v50 row_ror:4 row_mask:0xf bank_mask:0xf bound_ctrl:1
	ds_read_b128 v[102:105], v22 offset:3584
	ds_read_b128 v[78:81], v22 offset:4096
	v_add_f32_dpp v50, v50, v50 row_ror:2 row_mask:0xf bank_mask:0xf bound_ctrl:1
	ds_read_b128 v[118:121], v22 offset:4352
	ds_read_b32 v136, v51 offset:3840
	v_add_f32_dpp v50, v50, v50 row_ror:1 row_mask:0xf bank_mask:0xf bound_ctrl:1
	v_pk_fma_f32 v[14:15], v[50:51], v[110:111], v[94:95] op_sel_hi:[0,1,1] neg_lo:[1,0,0] neg_hi:[1,0,0]
	v_pk_fma_f32 v[16:17], v[50:51], v[112:113], v[134:135] op_sel_hi:[0,1,1] neg_lo:[1,0,0] neg_hi:[1,0,0]
	v_pk_mul_f32 v[94:95], v[14:15], v[122:123]
	s_waitcnt lgkmcnt(6)
	v_pk_mul_f32 v[90:91], v[14:15], v[82:83]
	v_pk_fma_f32 v[94:95], v[16:17], v[124:125], v[94:95]
	v_pk_fma_f32 v[90:91], v[16:17], v[84:85], v[90:91]
	v_add_f32_e32 v19, v94, v95
	v_pk_fma_f32 v[94:95], v[98:99], v[14:15], v[14:15] neg_lo:[1,0,0] neg_hi:[1,0,0]
	v_pk_fma_f32 v[134:135], v[100:101], v[16:17], v[16:17] neg_lo:[1,0,0] neg_hi:[1,0,0]
	v_add_f32_e32 v50, v90, v91
	v_pk_fma_f32 v[94:95], v[138:139], v[106:107], v[94:95] op_sel_hi:[0,1,1]
	v_pk_fma_f32 v[134:135], v[138:139], v[108:109], v[134:135] op_sel_hi:[0,1,1]
	v_add_f32_dpp v50, v50, v50 row_ror:8 row_mask:0xf bank_mask:0xf bound_ctrl:1
	ds_read_b128 v[122:125], v22 offset:4608
	ds_read_b128 v[98:101], v22 offset:4864
	v_add_f32_dpp v50, v50, v50 row_ror:4 row_mask:0xf bank_mask:0xf bound_ctrl:1
	ds_read_b128 v[106:109], v22 offset:5120
	ds_read_b128 v[82:85], v22 offset:5632
	v_add_f32_dpp v50, v50, v50 row_ror:2 row_mask:0xf bank_mask:0xf bound_ctrl:1
	ds_read_b128 v[110:113], v22 offset:5888
	ds_read_b32 v138, v51 offset:5376
	v_add_f32_dpp v50, v50, v50 row_ror:1 row_mask:0xf bank_mask:0xf bound_ctrl:1
	v_pk_fma_f32 v[14:15], v[50:51], v[114:115], v[94:95] op_sel_hi:[0,1,1] neg_lo:[1,0,0] neg_hi:[1,0,0]
	v_pk_fma_f32 v[16:17], v[50:51], v[116:117], v[134:135] op_sel_hi:[0,1,1] neg_lo:[1,0,0] neg_hi:[1,0,0]
	v_pk_mul_f32 v[94:95], v[14:15], v[126:127]
	s_waitcnt lgkmcnt(6)
	v_pk_mul_f32 v[90:91], v[14:15], v[78:79]
	v_pk_fma_f32 v[94:95], v[16:17], v[128:129], v[94:95]
	v_pk_fma_f32 v[90:91], v[16:17], v[80:81], v[90:91]
	v_add_f32_e32 v21, v94, v95
	v_pk_fma_f32 v[94:95], v[86:87], v[14:15], v[14:15] neg_lo:[1,0,0] neg_hi:[1,0,0]
	v_pk_fma_f32 v[134:135], v[88:89], v[16:17], v[16:17] neg_lo:[1,0,0] neg_hi:[1,0,0]
	v_add_f32_e32 v50, v90, v91
	v_pk_fma_f32 v[94:95], v[136:137], v[102:103], v[94:95] op_sel_hi:[0,1,1]
	v_pk_fma_f32 v[134:135], v[136:137], v[104:105], v[134:135] op_sel_hi:[0,1,1]
	v_add_f32_dpp v50, v50, v50 row_ror:8 row_mask:0xf bank_mask:0xf bound_ctrl:1
	ds_read_b128 v[126:129], v22 offset:6144
	ds_read_b128 v[86:89], v22 offset:6400
	v_add_f32_dpp v50, v50, v50 row_ror:4 row_mask:0xf bank_mask:0xf bound_ctrl:1
	ds_read_b128 v[102:105], v22 offset:6656
	ds_read_b128 v[78:81], v22 offset:7168
	v_add_f32_dpp v50, v50, v50 row_ror:2 row_mask:0xf bank_mask:0xf bound_ctrl:1
	ds_read_b128 v[114:117], v22 offset:7424
	ds_read_b32 v136, v51 offset:6912
	v_add_f32_dpp v50, v50, v50 row_ror:1 row_mask:0xf bank_mask:0xf bound_ctrl:1
	v_pk_fma_f32 v[14:15], v[50:51], v[118:119], v[94:95] op_sel_hi:[0,1,1] neg_lo:[1,0,0] neg_hi:[1,0,0]
	v_pk_fma_f32 v[16:17], v[50:51], v[120:121], v[134:135] op_sel_hi:[0,1,1] neg_lo:[1,0,0] neg_hi:[1,0,0]
	v_pk_mul_f32 v[94:95], v[14:15], v[130:131]
	s_waitcnt lgkmcnt(6)
; #define LO2(v4) (__builtin_shufflevector(v4, v4, 0, 1))
; #define HI2(v4) (__builtin_shufflevector(v4, v4, 2, 3))
; __device__ __forceinline__ f32x2 fma2(f32x2 a, f32x2 b, f32x2 c) { return __builtin_elementwise_fma(a, b, c); }
; #define WKV_LOAD(d, s) do { const LAS float* p_ = bw + (s) * SCW; d.r = *(const LAS f32x4*)(p_); d.u = *(const LAS f32x4*)(p_ + 64); d.km = *(const LAS f32x4*)(p_ + 128); \
;                     d.kk = *(const LAS f32x4*)(p_ + 256); d.ka = *(const LAS f32x4*)(p_ + 320); d.v = bv[(s) * SCW]; } while (0)
; __device__ __forceinline__ void scan_phase(const Args& a, int e, LAS unsigned char* lds) {
;     ...
;                 for (int s = 0; s < TC; ++s) {
;                     if (s + 2 < TC) WKV_LOAD(in[(s + 2) % 3], s + 2);
;                     __builtin_amdgcn_sched_barrier(0);
;                     const WkvIn& x = in[s % 3];
;                     const f32x2 vv = {x.v, x.v};
;                     const f32x2 s2 = fma2(P1, HI2(x.kk), P0 * LO2(x.kk));
;                     const f32x2 T0 = fma2(vv, LO2(x.km), fma2(-LO2(x.u), P0, P0)), T1 = fma2(vv, HI2(x.km), fma2(-HI2(x.u), P1, P1));
;                     const float sa = rowsum16(s2.x + s2.y);
;                     const f32x2 ns = {-sa, -sa};
;                     P0 = fma2(ns, LO2(x.ka), T0); P1 = fma2(ns, HI2(x.ka), T1);
;                     const f32x2 o2 = fma2(P1, HI2(x.r), P0 * LO2(x.r));
;                     op[s] = o2.x + o2.y;
;                 }
	v_pk_mul_f32 v[90:91], v[14:15], v[82:83]
	v_pk_fma_f32 v[94:95], v[16:17], v[132:133], v[94:95]
	v_pk_fma_f32 v[90:91], v[16:17], v[84:85], v[90:91]
	v_add_f32_e32 v24, v94, v95
	v_pk_fma_f32 v[94:95], v[98:99], v[14:15], v[14:15] neg_lo:[1,0,0] neg_hi:[1,0,0]
	v_pk_fma_f32 v[134:135], v[100:101], v[16:17], v[16:17] neg_lo:[1,0,0] neg_hi:[1,0,0]
	v_add_f32_e32 v50, v90, v91
	v_pk_fma_f32 v[94:95], v[138:139], v[106:107], v[94:95] op_sel_hi:[0,1,1]
	v_pk_fma_f32 v[134:135], v[138:139], v[108:109], v[134:135] op_sel_hi:[0,1,1]
	v_add_f32_dpp v50, v50, v50 row_ror:8 row_mask:0xf bank_mask:0xf bound_ctrl:1
	ds_read_b128 v[130:133], v22 offset:7680
	ds_read_b128 v[98:101], v22 offset:7936
	v_add_f32_dpp v50, v50, v50 row_ror:4 row_mask:0xf bank_mask:0xf bound_ctrl:1
	ds_read_b128 v[106:109], v22 offset:8192
	ds_read_b128 v[82:85], v22 offset:8704
	v_add_f32_dpp v50, v50, v50 row_ror:2 row_mask:0xf bank_mask:0xf bound_ctrl:1
	ds_read_b128 v[118:121], v22 offset:8960
	ds_read_b32 v138, v51 offset:8448
	v_add_f32_dpp v50, v50, v50 row_ror:1 row_mask:0xf bank_mask:0xf bound_ctrl:1
	v_pk_fma_f32 v[14:15], v[50:51], v[110:111], v[94:95] op_sel_hi:[0,1,1] neg_lo:[1,0,0] neg_hi:[1,0,0]
	v_pk_fma_f32 v[16:17], v[50:51], v[112:113], v[134:135] op_sel_hi:[0,1,1] neg_lo:[1,0,0] neg_hi:[1,0,0]
	v_pk_mul_f32 v[94:95], v[14:15], v[122:123]
	s_waitcnt lgkmcnt(6)
	v_pk_mul_f32 v[90:91], v[14:15], v[78:79]
	v_pk_fma_f32 v[94:95], v[16:17], v[124:125], v[94:95]
	v_pk_fma_f32 v[90:91], v[16:17], v[80:81], v[90:91]
	v_add_f32_e32 v25, v94, v95
	v_pk_fma_f32 v[94:95], v[86:87], v[14:15], v[14:15] neg_lo:[1,0,0] neg_hi:[1,0,0]
	v_pk_fma_f32 v[134:135], v[88:89], v[16:17], v[16:17] neg_lo:[1,0,0] neg_hi:[1,0,0]
	v_add_f32_e32 v50, v90, v91
	v_pk_fma_f32 v[94:95], v[136:137], v[102:103], v[94:95] op_sel_hi:[0,1,1]
	v_pk_fma_f32 v[134:135], v[136:137], v[104:105], v[134:135] op_sel_hi:[0,1,1]
	v_add_f32_dpp v50, v50, v50 row_ror:8 row_mask:0xf bank_mask:0xf bound_ctrl:1
	ds_read_b128 v[122:125], v22 offset:9216
	ds_read_b128 v[86:89], v22 offset:9472
	v_add_f32_dpp v50, v50, v50 row_ror:4 row_mask:0xf bank_mask:0xf bound_ctrl:1
	ds_read_b128 v[102:105], v22 offset:9728
	ds_read_b128 v[78:81], v22 offset:10240
	v_add_f32_dpp v50, v50, v50 row_ror:2 row_mask:0xf bank_mask:0xf bound_ctrl:1
	ds_read_b128 v[110:113], v22 offset:10496
	ds_read_b32 v136, v51 offset:9984
	v_add_f32_dpp v50, v50, v50 row_ror:1 row_mask:0xf bank_mask:0xf bound_ctrl:1
	v_pk_fma_f32 v[14:15], v[50:51], v[114:115], v[94:95] op_sel_hi:[0,1,1] neg_lo:[1,0,0] neg_hi:[1,0,0]
	v_pk_fma_f32 v[16:17], v[50:51], v[116:117], v[134:135] op_sel_hi:[0,1,1] neg_lo:[1,0,0] neg_hi:[1,0,0]
	v_pk_mul_f32 v[94:95], v[14:15], v[126:127]
	s_waitcnt lgkmcnt(6)
	v_pk_mul_f32 v[90:91], v[14:15], v[82:83]
	v_pk_fma_f32 v[94:95], v[16:17], v[128:129], v[94:95]
	v_pk_fma_f32 v[90:91], v[16:17], v[84:85], v[90:91]
	v_add_f32_e32 v43, v94, v95
	v_pk_fma_f32 v[94:95], v[98:99], v[14:15], v[14:15] neg_lo:[1,0,0] neg_hi:[1,0,0]
	v_pk_fma_f32 v[134:135], v[100:101], v[16:17], v[16:17] neg_lo:[1,0,0] neg_hi:[1,0,0]
	v_add_f32_e32 v50, v90, v91
	v_pk_fma_f32 v[94:95], v[138:139], v[106:107], v[94:95] op_sel_hi:[0,1,1]
	v_pk_fma_f32 v[134:135], v[138:139], v[108:109], v[134:135] op_sel_hi:[0,1,1]
	v_add_f32_dpp v50, v50, v50 row_ror:8 row_mask:0xf bank_mask:0xf bound_ctrl:1
	ds_read_b128 v[126:129], v22 offset:10752
	ds_read_b128 v[98:101], v22 offset:11008
	v_add_f32_dpp v50, v50, v50 row_ror:4 row_mask:0xf bank_mask:0xf bound_ctrl:1
	ds_read_b128 v[106:109], v22 offset:11264
	ds_read_b128 v[82:85], v22 offset:11776
	v_add_f32_dpp v50, v50, v50 row_ror:2 row_mask:0xf bank_mask:0xf bound_ctrl:1
	ds_read_b128 v[114:117], v22 offset:12032
	ds_read_b32 v138, v51 offset:11520
	v_add_f32_dpp v50, v50, v50 row_ror:1 row_mask:0xf bank_mask:0xf bound_ctrl:1
	v_pk_fma_f32 v[14:15], v[50:51], v[118:119], v[94:95] op_sel_hi:[0,1,1] neg_lo:[1,0,0] neg_hi:[1,0,0]
	v_pk_fma_f32 v[16:17], v[50:51], v[120:121], v[134:135] op_sel_hi:[0,1,1] neg_lo:[1,0,0] neg_hi:[1,0,0]
	v_pk_mul_f32 v[94:95], v[14:15], v[130:131]
	s_waitcnt lgkmcnt(6)
	v_pk_mul_f32 v[90:91], v[14:15], v[78:79]
	v_pk_fma_f32 v[94:95], v[16:17], v[132:133], v[94:95]
	v_pk_fma_f32 v[90:91], v[16:17], v[80:81], v[90:91]
	v_add_f32_e32 v45, v94, v95
	v_pk_fma_f32 v[94:95], v[86:87], v[14:15], v[14:15] neg_lo:[1,0,0] neg_hi:[1,0,0]
	v_pk_fma_f32 v[134:135], v[88:89], v[16:17], v[16:17] neg_lo:[1,0,0] neg_hi:[1,0,0]
	v_add_f32_e32 v50, v90, v91
	v_pk_fma_f32 v[94:95], v[136:137], v[102:103], v[94:95] op_sel_hi:[0,1,1]
	v_pk_fma_f32 v[134:135], v[136:137], v[104:105], v[134:135] op_sel_hi:[0,1,1]
	v_add_f32_dpp v50, v50, v50 row_ror:8 row_mask:0xf bank_mask:0xf bound_ctrl:1
	ds_read_b128 v[130:133], v22 offset:12288
	ds_read_b128 v[86:89], v22 offset:12544
	v_add_f32_dpp v50, v50, v50 row_ror:4 row_mask:0xf bank_mask:0xf bound_ctrl:1
	ds_read_b128 v[102:105], v22 offset:12800
	ds_read_b128 v[78:81], v22 offset:13312
	v_add_f32_dpp v50, v50, v50 row_ror:2 row_mask:0xf bank_mask:0xf bound_ctrl:1
	ds_read_b128 v[118:121], v22 offset:13568
	ds_read_b32 v136, v51 offset:13056
	v_add_f32_dpp v50, v50, v50 row_ror:1 row_mask:0xf bank_mask:0xf bound_ctrl:1
	v_pk_fma_f32 v[14:15], v[50:51], v[110:111], v[94:95] op_sel_hi:[0,1,1] neg_lo:[1,0,0] neg_hi:[1,0,0]
	v_pk_fma_f32 v[16:17], v[50:51], v[112:113], v[134:135] op_sel_hi:[0,1,1] neg_lo:[1,0,0] neg_hi:[1,0,0]
	v_pk_mul_f32 v[94:95], v[14:15], v[122:123]
	s_waitcnt lgkmcnt(6)
; #define TR_DPP(x, ctrl) __builtin_bit_cast(float, __builtin_amdgcn_update_dpp(0, __builtin_bit_cast(int, x), ctrl, 0xf, 0xf, false))
; #define LO2(v4) (__builtin_shufflevector(v4, v4, 0, 1))
; #define HI2(v4) (__builtin_shufflevector(v4, v4, 2, 3))
; __device__ __forceinline__ f32x2 fma2(f32x2 a, f32x2 b, f32x2 c) { return __builtin_elementwise_fma(a, b, c); }
; #define WKV_LOAD(d, s) do { const LAS float* p_ = bw + (s) * SCW; d.r = *(const LAS f32x4*)(p_); d.u = *(const LAS f32x4*)(p_ + 64); d.km = *(const LAS f32x4*)(p_ + 128); \
;                     d.kk = *(const LAS f32x4*)(p_ + 256); d.ka = *(const LAS f32x4*)(p_ + 320); d.v = bv[(s) * SCW]; } while (0)
; __device__ __forceinline__ float transpose_reduce16(const float* p, int g) {
;     ...
;     for (int i = 0; i < 8; ++i) { const float keep = h1 ? p[i + 8] : p[i], send = h1 ? p[i] : p[i + 8]; q[i] = keep + TR_DPP(send, 0x140); }
; __device__ __forceinline__ void scan_phase(const Args& a, int e, LAS unsigned char* lds) {
;     ...
;                 for (int s = 0; s < TC; ++s) {
;                     if (s + 2 < TC) WKV_LOAD(in[(s + 2) % 3], s + 2);
;                     __builtin_amdgcn_sched_barrier(0);
;                     const WkvIn& x = in[s % 3];
;                     const f32x2 vv = {x.v, x.v};
;                     const f32x2 s2 = fma2(P1, HI2(x.kk), P0 * LO2(x.kk));
;                     const f32x2 T0 = fma2(vv, LO2(x.km), fma2(-LO2(x.u), P0, P0)), T1 = fma2(vv, HI2(x.km), fma2(-HI2(x.u), P1, P1));
;                     const float sa = rowsum16(s2.x + s2.y);
;                     const f32x2 ns = {-sa, -sa};
;                     P0 = fma2(ns, LO2(x.ka), T0); P1 = fma2(ns, HI2(x.ka), T1);
;                     const f32x2 o2 = fma2(P1, HI2(x.r), P0 * LO2(x.r));
;                     op[s] = o2.x + o2.y;
;                 }
	v_pk_mul_f32 v[90:91], v[14:15], v[82:83]
	v_pk_fma_f32 v[94:95], v[16:17], v[124:125], v[94:95]
	v_pk_fma_f32 v[90:91], v[16:17], v[84:85], v[90:91]
	v_add_f32_e32 v48, v94, v95
	v_pk_fma_f32 v[94:95], v[98:99], v[14:15], v[14:15] neg_lo:[1,0,0] neg_hi:[1,0,0]
	v_pk_fma_f32 v[134:135], v[100:101], v[16:17], v[16:17] neg_lo:[1,0,0] neg_hi:[1,0,0]
	v_add_f32_e32 v50, v90, v91
	v_pk_fma_f32 v[94:95], v[138:139], v[106:107], v[94:95] op_sel_hi:[0,1,1]
	v_pk_fma_f32 v[134:135], v[138:139], v[108:109], v[134:135] op_sel_hi:[0,1,1]
	v_add_f32_dpp v50, v50, v50 row_ror:8 row_mask:0xf bank_mask:0xf bound_ctrl:1
	ds_read_b128 v[122:125], v22 offset:13824
	ds_read_b128 v[98:101], v22 offset:14080
	v_add_f32_dpp v50, v50, v50 row_ror:4 row_mask:0xf bank_mask:0xf bound_ctrl:1
	ds_read_b128 v[106:109], v22 offset:14336
	ds_read_b128 v[82:85], v22 offset:14848
	v_add_f32_dpp v50, v50, v50 row_ror:2 row_mask:0xf bank_mask:0xf bound_ctrl:1
	ds_read_b128 v[110:113], v22 offset:15104
	ds_read_b32 v138, v51 offset:14592
	v_add_f32_dpp v50, v50, v50 row_ror:1 row_mask:0xf bank_mask:0xf bound_ctrl:1
	v_pk_fma_f32 v[14:15], v[50:51], v[114:115], v[94:95] op_sel_hi:[0,1,1] neg_lo:[1,0,0] neg_hi:[1,0,0]
	v_pk_fma_f32 v[16:17], v[50:51], v[116:117], v[134:135] op_sel_hi:[0,1,1] neg_lo:[1,0,0] neg_hi:[1,0,0]
	v_pk_mul_f32 v[94:95], v[14:15], v[126:127]
	s_waitcnt lgkmcnt(6)
	v_pk_mul_f32 v[90:91], v[14:15], v[78:79]
	v_pk_fma_f32 v[94:95], v[16:17], v[128:129], v[94:95]
	v_pk_fma_f32 v[90:91], v[16:17], v[80:81], v[90:91]
	v_add_f32_e32 v49, v94, v95
	v_pk_fma_f32 v[94:95], v[86:87], v[14:15], v[14:15] neg_lo:[1,0,0] neg_hi:[1,0,0]
	v_pk_fma_f32 v[134:135], v[88:89], v[16:17], v[16:17] neg_lo:[1,0,0] neg_hi:[1,0,0]
	v_add_f32_e32 v50, v90, v91
	v_pk_fma_f32 v[94:95], v[136:137], v[102:103], v[94:95] op_sel_hi:[0,1,1]
	v_pk_fma_f32 v[134:135], v[136:137], v[104:105], v[134:135] op_sel_hi:[0,1,1]
	v_add_f32_dpp v50, v50, v50 row_ror:8 row_mask:0xf bank_mask:0xf bound_ctrl:1
	ds_read_b128 v[126:129], v22 offset:15360
	ds_read_b128 v[86:89], v22 offset:15616
	v_add_f32_dpp v50, v50, v50 row_ror:4 row_mask:0xf bank_mask:0xf bound_ctrl:1
	ds_read_b128 v[102:105], v22 offset:15872
	ds_read_b128 v[78:81], v22 offset:16384
	v_add_f32_dpp v50, v50, v50 row_ror:2 row_mask:0xf bank_mask:0xf bound_ctrl:1
	ds_read_b128 v[114:117], v22 offset:16640
	ds_read_b32 v136, v51 offset:16128
	v_add_f32_dpp v50, v50, v50 row_ror:1 row_mask:0xf bank_mask:0xf bound_ctrl:1
	v_pk_fma_f32 v[14:15], v[50:51], v[118:119], v[94:95] op_sel_hi:[0,1,1] neg_lo:[1,0,0] neg_hi:[1,0,0]
	v_pk_fma_f32 v[16:17], v[50:51], v[120:121], v[134:135] op_sel_hi:[0,1,1] neg_lo:[1,0,0] neg_hi:[1,0,0]
	v_pk_mul_f32 v[94:95], v[14:15], v[130:131]
	s_waitcnt lgkmcnt(6)
	v_pk_mul_f32 v[90:91], v[14:15], v[82:83]
	v_pk_fma_f32 v[94:95], v[16:17], v[132:133], v[94:95]
	v_pk_fma_f32 v[90:91], v[16:17], v[84:85], v[90:91]
	v_add_f32_e32 v137, v94, v95
	v_pk_fma_f32 v[94:95], v[98:99], v[14:15], v[14:15] neg_lo:[1,0,0] neg_hi:[1,0,0]
	v_pk_fma_f32 v[134:135], v[100:101], v[16:17], v[16:17] neg_lo:[1,0,0] neg_hi:[1,0,0]
	v_add_f32_e32 v50, v90, v91
	v_pk_fma_f32 v[94:95], v[138:139], v[106:107], v[94:95] op_sel_hi:[0,1,1]
	v_pk_fma_f32 v[134:135], v[138:139], v[108:109], v[134:135] op_sel_hi:[0,1,1]
	v_add_f32_dpp v50, v50, v50 row_ror:8 row_mask:0xf bank_mask:0xf bound_ctrl:1
	ds_read_b128 v[130:133], v22 offset:16896
	ds_read_b128 v[98:101], v22 offset:17152
	v_cndmask_b32_e64 v23, v137, v19, s[42:43]
	v_cndmask_b32_e64 v19, v19, v137, s[42:43]
	v_add_f32_dpp v50, v50, v50 row_ror:4 row_mask:0xf bank_mask:0xf bound_ctrl:1
	ds_read_b128 v[106:109], v22 offset:17408
	ds_read_b128 v[82:85], v22 offset:17920
	v_add_f32_dpp v50, v50, v50 row_ror:2 row_mask:0xf bank_mask:0xf bound_ctrl:1
	ds_read_b128 v[118:121], v22 offset:18176
	ds_read_b32 v138, v51 offset:17664
	v_add_f32_dpp v19, v19, v23 row_mirror row_mask:0xf bank_mask:0xf bound_ctrl:1
	v_add_f32_dpp v50, v50, v50 row_ror:1 row_mask:0xf bank_mask:0xf bound_ctrl:1
	v_pk_fma_f32 v[14:15], v[50:51], v[110:111], v[94:95] op_sel_hi:[0,1,1] neg_lo:[1,0,0] neg_hi:[1,0,0]
	v_pk_fma_f32 v[16:17], v[50:51], v[112:113], v[134:135] op_sel_hi:[0,1,1] neg_lo:[1,0,0] neg_hi:[1,0,0]
	v_pk_mul_f32 v[94:95], v[14:15], v[122:123]
	s_waitcnt lgkmcnt(6)
	v_pk_mul_f32 v[90:91], v[14:15], v[78:79]
	v_pk_fma_f32 v[94:95], v[16:17], v[124:125], v[94:95]
	v_pk_fma_f32 v[90:91], v[16:17], v[80:81], v[90:91]
	v_add_f32_e32 v139, v94, v95
	v_pk_fma_f32 v[94:95], v[86:87], v[14:15], v[14:15] neg_lo:[1,0,0] neg_hi:[1,0,0]
	v_pk_fma_f32 v[134:135], v[88:89], v[16:17], v[16:17] neg_lo:[1,0,0] neg_hi:[1,0,0]
	v_add_f32_e32 v50, v90, v91
	v_pk_fma_f32 v[94:95], v[136:137], v[102:103], v[94:95] op_sel_hi:[0,1,1]
	v_pk_fma_f32 v[134:135], v[136:137], v[104:105], v[134:135] op_sel_hi:[0,1,1]
	v_add_f32_dpp v50, v50, v50 row_ror:8 row_mask:0xf bank_mask:0xf bound_ctrl:1
	ds_read_b128 v[122:125], v22 offset:18432
	ds_read_b128 v[86:89], v22 offset:18688
	v_cndmask_b32_e64 v23, v139, v21, s[42:43]
	v_cndmask_b32_e64 v21, v21, v139, s[42:43]
	v_add_f32_dpp v50, v50, v50 row_ror:4 row_mask:0xf bank_mask:0xf bound_ctrl:1
	ds_read_b128 v[102:105], v22 offset:18944
	ds_read_b128 v[78:81], v22 offset:19456
	v_add_f32_dpp v50, v50, v50 row_ror:2 row_mask:0xf bank_mask:0xf bound_ctrl:1
	ds_read_b128 v[110:113], v22 offset:19712
	ds_read_b32 v136, v51 offset:19200
	v_add_f32_dpp v21, v21, v23 row_mirror row_mask:0xf bank_mask:0xf bound_ctrl:1
	v_add_f32_dpp v50, v50, v50 row_ror:1 row_mask:0xf bank_mask:0xf bound_ctrl:1
	v_pk_fma_f32 v[14:15], v[50:51], v[114:115], v[94:95] op_sel_hi:[0,1,1] neg_lo:[1,0,0] neg_hi:[1,0,0]
	v_pk_fma_f32 v[16:17], v[50:51], v[116:117], v[134:135] op_sel_hi:[0,1,1] neg_lo:[1,0,0] neg_hi:[1,0,0]
	v_pk_mul_f32 v[94:95], v[14:15], v[126:127]
	s_waitcnt lgkmcnt(6)
; #define TR_DPP(x, ctrl) __builtin_bit_cast(float, __builtin_amdgcn_update_dpp(0, __builtin_bit_cast(int, x), ctrl, 0xf, 0xf, false))
; #define LO2(v4) (__builtin_shufflevector(v4, v4, 0, 1))
; #define HI2(v4) (__builtin_shufflevector(v4, v4, 2, 3))
; __device__ __forceinline__ f32x2 fma2(f32x2 a, f32x2 b, f32x2 c) { return __builtin_elementwise_fma(a, b, c); }
; #define WKV_LOAD(d, s) do { const LAS float* p_ = bw + (s) * SCW; d.r = *(const LAS f32x4*)(p_); d.u = *(const LAS f32x4*)(p_ + 64); d.km = *(const LAS f32x4*)(p_ + 128); \
;                     d.kk = *(const LAS f32x4*)(p_ + 256); d.ka = *(const LAS f32x4*)(p_ + 320); d.v = bv[(s) * SCW]; } while (0)
; __device__ __forceinline__ float transpose_reduce16(const float* p, int g) {
;     const bool h1 = (g & 8) != 0, h2 = (g & 4) != 0, h3 = (g & 2) != 0, h4 = (g & 1) != 0;
;     float q[8], r[4], t[2];
; #pragma unroll
;     for (int i = 0; i < 8; ++i) { const float keep = h1 ? p[i + 8] : p[i], send = h1 ? p[i] : p[i + 8]; q[i] = keep + TR_DPP(send, 0x140); }
; __device__ __forceinline__ void scan_phase(const Args& a, int e, LAS unsigned char* lds) {
;     ...
;                 for (int s = 0; s < TC; ++s) {
;                     if (s + 2 < TC) WKV_LOAD(in[(s + 2) % 3], s + 2);
;                     __builtin_amdgcn_sched_barrier(0);
;                     const WkvIn& x = in[s % 3];
;                     const f32x2 vv = {x.v, x.v};
;                     const f32x2 s2 = fma2(P1, HI2(x.kk), P0 * LO2(x.kk));
;                     const f32x2 T0 = fma2(vv, LO2(x.km), fma2(-LO2(x.u), P0, P0)), T1 = fma2(vv, HI2(x.km), fma2(-HI2(x.u), P1, P1));
;                     const float sa = rowsum16(s2.x + s2.y);
;                     const f32x2 ns = {-sa, -sa};
;                     P0 = fma2(ns, LO2(x.ka), T0); P1 = fma2(ns, HI2(x.ka), T1);
;                     const f32x2 o2 = fma2(P1, HI2(x.r), P0 * LO2(x.r));
;                     op[s] = o2.x + o2.y;
;                 }
	v_pk_mul_f32 v[90:91], v[14:15], v[82:83]
	v_pk_fma_f32 v[94:95], v[16:17], v[128:129], v[94:95]
	v_pk_fma_f32 v[90:91], v[16:17], v[84:85], v[90:91]
	v_add_f32_e32 v141, v94, v95
	v_pk_fma_f32 v[94:95], v[98:99], v[14:15], v[14:15] neg_lo:[1,0,0] neg_hi:[1,0,0]
	v_pk_fma_f32 v[134:135], v[100:101], v[16:17], v[16:17] neg_lo:[1,0,0] neg_hi:[1,0,0]
	v_add_f32_e32 v50, v90, v91
	v_pk_fma_f32 v[94:95], v[138:139], v[106:107], v[94:95] op_sel_hi:[0,1,1]
	v_pk_fma_f32 v[134:135], v[138:139], v[108:109], v[134:135] op_sel_hi:[0,1,1]
	v_add_f32_dpp v50, v50, v50 row_ror:8 row_mask:0xf bank_mask:0xf bound_ctrl:1
	ds_read_b128 v[126:129], v22 offset:19968
	ds_read_b128 v[98:101], v22 offset:20224
	v_cndmask_b32_e64 v23, v141, v24, s[42:43]
	v_cndmask_b32_e64 v24, v24, v141, s[42:43]
	v_add_f32_dpp v50, v50, v50 row_ror:4 row_mask:0xf bank_mask:0xf bound_ctrl:1
	ds_read_b128 v[106:109], v22 offset:20480
	ds_read_b128 v[82:85], v22 offset:20992
	v_add_f32_dpp v50, v50, v50 row_ror:2 row_mask:0xf bank_mask:0xf bound_ctrl:1
	ds_read_b128 v[114:117], v22 offset:21248
	ds_read_b32 v138, v51 offset:20736
	v_add_f32_dpp v23, v24, v23 row_mirror row_mask:0xf bank_mask:0xf bound_ctrl:1
	v_add_f32_dpp v50, v50, v50 row_ror:1 row_mask:0xf bank_mask:0xf bound_ctrl:1
	v_pk_fma_f32 v[14:15], v[50:51], v[118:119], v[94:95] op_sel_hi:[0,1,1] neg_lo:[1,0,0] neg_hi:[1,0,0]
	v_pk_fma_f32 v[16:17], v[50:51], v[120:121], v[134:135] op_sel_hi:[0,1,1] neg_lo:[1,0,0] neg_hi:[1,0,0]
	v_pk_mul_f32 v[94:95], v[14:15], v[130:131]
	s_waitcnt lgkmcnt(6)
	v_pk_mul_f32 v[90:91], v[14:15], v[78:79]
	v_pk_fma_f32 v[94:95], v[16:17], v[132:133], v[94:95]
	v_pk_fma_f32 v[90:91], v[16:17], v[80:81], v[90:91]
	v_add_f32_e32 v142, v94, v95
	v_pk_fma_f32 v[94:95], v[86:87], v[14:15], v[14:15] neg_lo:[1,0,0] neg_hi:[1,0,0]
	v_pk_fma_f32 v[134:135], v[88:89], v[16:17], v[16:17] neg_lo:[1,0,0] neg_hi:[1,0,0]
	v_add_f32_e32 v50, v90, v91
	v_pk_fma_f32 v[94:95], v[136:137], v[102:103], v[94:95] op_sel_hi:[0,1,1]
	v_pk_fma_f32 v[134:135], v[136:137], v[104:105], v[134:135] op_sel_hi:[0,1,1]
	v_add_f32_dpp v50, v50, v50 row_ror:8 row_mask:0xf bank_mask:0xf bound_ctrl:1
	ds_read_b128 v[130:133], v22 offset:21504
	ds_read_b128 v[86:89], v22 offset:21760
	v_cndmask_b32_e64 v24, v142, v25, s[42:43]
	v_cndmask_b32_e64 v25, v25, v142, s[42:43]
	v_add_f32_dpp v50, v50, v50 row_ror:4 row_mask:0xf bank_mask:0xf bound_ctrl:1
	ds_read_b128 v[102:105], v22 offset:22016
	ds_read_b128 v[78:81], v22 offset:22528
	s_lshl_b32 s15, s14, 4
	s_xor_b32 s15, s15, 16
	v_or_b32_e32 v93, s15, v54
	v_add_f32_dpp v50, v50, v50 row_ror:2 row_mask:0xf bank_mask:0xf bound_ctrl:1
	ds_read_b128 v[118:121], v22 offset:22784
	ds_read_b32 v136, v51 offset:22272
	v_add_f32_dpp v24, v25, v24 row_mirror row_mask:0xf bank_mask:0xf bound_ctrl:1
	v_add_u32_e32 v97, s15, v53
	v_mad_u32_u24 v93, v93, v67, v68
	v_mad_u32_u24 v97, v97, v67, v69
	v_add_f32_dpp v50, v50, v50 row_ror:1 row_mask:0xf bank_mask:0xf bound_ctrl:1
	v_pk_fma_f32 v[14:15], v[50:51], v[110:111], v[94:95] op_sel_hi:[0,1,1] neg_lo:[1,0,0] neg_hi:[1,0,0]
	v_pk_fma_f32 v[16:17], v[50:51], v[112:113], v[134:135] op_sel_hi:[0,1,1] neg_lo:[1,0,0] neg_hi:[1,0,0]
	v_pk_mul_f32 v[94:95], v[14:15], v[122:123]
	s_waitcnt lgkmcnt(6)
	v_pk_mul_f32 v[90:91], v[14:15], v[82:83]
	v_pk_fma_f32 v[94:95], v[16:17], v[124:125], v[94:95]
	v_pk_fma_f32 v[90:91], v[16:17], v[84:85], v[90:91]
	v_add_f32_e32 v140, v94, v95
	v_pk_fma_f32 v[94:95], v[98:99], v[14:15], v[14:15] neg_lo:[1,0,0] neg_hi:[1,0,0]
	v_pk_fma_f32 v[134:135], v[100:101], v[16:17], v[16:17] neg_lo:[1,0,0] neg_hi:[1,0,0]
	v_add_f32_e32 v50, v90, v91
	v_pk_fma_f32 v[94:95], v[138:139], v[106:107], v[94:95] op_sel_hi:[0,1,1]
	v_pk_fma_f32 v[134:135], v[138:139], v[108:109], v[134:135] op_sel_hi:[0,1,1]
	v_add_f32_dpp v50, v50, v50 row_ror:8 row_mask:0xf bank_mask:0xf bound_ctrl:1
	ds_read_b128 v[122:125], v22 offset:23040
	ds_read_b128 v[98:101], v22 offset:23296
	v_cndmask_b32_e64 v25, v140, v43, s[42:43]
	v_cndmask_b32_e64 v43, v43, v140, s[42:43]
	v_add_f32_dpp v50, v50, v50 row_ror:4 row_mask:0xf bank_mask:0xf bound_ctrl:1
	ds_read_b128 v[106:109], v22 offset:23552
	ds_read_b128 v[82:85], v22 offset:24064
	v_add_f32_dpp v50, v50, v50 row_ror:2 row_mask:0xf bank_mask:0xf bound_ctrl:1
	ds_read_b128 v[110:113], v22 offset:24320
	ds_read_b32 v138, v51 offset:23808
	v_add_f32_dpp v25, v43, v25 row_mirror row_mask:0xf bank_mask:0xf bound_ctrl:1
	v_add_f32_dpp v50, v50, v50 row_ror:1 row_mask:0xf bank_mask:0xf bound_ctrl:1
	v_pk_fma_f32 v[14:15], v[50:51], v[114:115], v[94:95] op_sel_hi:[0,1,1] neg_lo:[1,0,0] neg_hi:[1,0,0]
	v_pk_fma_f32 v[16:17], v[50:51], v[116:117], v[134:135] op_sel_hi:[0,1,1] neg_lo:[1,0,0] neg_hi:[1,0,0]
	v_pk_mul_f32 v[94:95], v[14:15], v[126:127]
	s_waitcnt lgkmcnt(6)
; #define TR_DPP(x, ctrl) __builtin_bit_cast(float, __builtin_amdgcn_update_dpp(0, __builtin_bit_cast(int, x), ctrl, 0xf, 0xf, false))
; __device__ __forceinline__ float transpose_reduce16(const float* p, int g) {
;     const bool h1 = (g & 8) != 0, h2 = (g & 4) != 0, h3 = (g & 2) != 0, h4 = (g & 1) != 0;
;     float q[8], r[4], t[2];
; #pragma unroll
;     for (int i = 0; i < 8; ++i) { const float keep = h1 ? p[i + 8] : p[i], send = h1 ? p[i] : p[i + 8]; q[i] = keep + TR_DPP(send, 0x140); }
; #pragma unroll
;     for (int i = 0; i < 4; ++i) { const float keep = h2 ? q[i + 4] : q[i], send = h2 ? q[i] : q[i + 4]; r[i] = keep + TR_DPP(send, 0x141); }
; #pragma unroll
;     for (int i = 0; i < 2; ++i) { const float keep = h3 ? r[i + 2] : r[i], send = h3 ? r[i] : r[i + 2]; t[i] = keep + TR_DPP(send, 0x4E); }
;     const float keep = h4 ? t[1] : t[0], send = h4 ? t[0] : t[1];
;     return keep + TR_DPP(send, 0xB1);
	v_pk_mul_f32 v[90:91], v[14:15], v[78:79]
	v_pk_fma_f32 v[94:95], v[16:17], v[128:129], v[94:95]
	v_pk_fma_f32 v[90:91], v[16:17], v[80:81], v[90:91]
	v_add_f32_e32 v96, v94, v95
	v_pk_fma_f32 v[94:95], v[86:87], v[14:15], v[14:15] neg_lo:[1,0,0] neg_hi:[1,0,0]
	v_pk_fma_f32 v[134:135], v[88:89], v[16:17], v[16:17] neg_lo:[1,0,0] neg_hi:[1,0,0]
	v_add_f32_e32 v50, v90, v91
	v_pk_fma_f32 v[94:95], v[136:137], v[102:103], v[94:95] op_sel_hi:[0,1,1]
	v_pk_fma_f32 v[134:135], v[136:137], v[104:105], v[134:135] op_sel_hi:[0,1,1]
	v_add_f32_dpp v50, v50, v50 row_ror:8 row_mask:0xf bank_mask:0xf bound_ctrl:1
	v_cndmask_b32_e64 v43, v96, v45, s[42:43]
	v_cndmask_b32_e64 v45, v45, v96, s[42:43]
	v_add_u32_e32 v51, s15, v31
	v_add_f32_dpp v50, v50, v50 row_ror:4 row_mask:0xf bank_mask:0xf bound_ctrl:1
	s_waitcnt vmcnt(0)
	v_lshlrev_b32_e32 v114, 16, v6
	v_and_b32_e32 v115, 0xffff0000, v6
	v_lshlrev_b32_e32 v116, 16, v7
	v_and_b32_e32 v117, 0xffff0000, v7
	v_add_f32_dpp v50, v50, v50 row_ror:2 row_mask:0xf bank_mask:0xf bound_ctrl:1
	v_add_f32_dpp v43, v45, v43 row_mirror row_mask:0xf bank_mask:0xf bound_ctrl:1
	v_lshlrev_b32_e32 v126, 16, v8
	v_and_b32_e32 v127, 0xffff0000, v8
	v_lshlrev_b32_e32 v128, 16, v9
	v_and_b32_e32 v129, 0xffff0000, v9
	v_mad_u32_u24 v51, v51, v67, v70
	v_add_f32_dpp v50, v50, v50 row_ror:1 row_mask:0xf bank_mask:0xf bound_ctrl:1
	v_pk_fma_f32 v[14:15], v[50:51], v[118:119], v[94:95] op_sel_hi:[0,1,1] neg_lo:[1,0,0] neg_hi:[1,0,0]
	v_pk_fma_f32 v[16:17], v[50:51], v[120:121], v[134:135] op_sel_hi:[0,1,1] neg_lo:[1,0,0] neg_hi:[1,0,0]
	v_pk_mul_f32 v[94:95], v[14:15], v[130:131]
	s_waitcnt lgkmcnt(0)
	v_pk_mul_f32 v[90:91], v[14:15], v[82:83]
	v_pk_fma_f32 v[94:95], v[16:17], v[132:133], v[94:95]
	v_pk_fma_f32 v[90:91], v[16:17], v[84:85], v[90:91]
	v_add_f32_e32 v92, v94, v95
	v_pk_fma_f32 v[94:95], v[98:99], v[14:15], v[14:15] neg_lo:[1,0,0] neg_hi:[1,0,0]
	v_pk_fma_f32 v[134:135], v[100:101], v[16:17], v[16:17] neg_lo:[1,0,0] neg_hi:[1,0,0]
	v_add_f32_e32 v50, v90, v91
	v_pk_fma_f32 v[94:95], v[138:139], v[106:107], v[94:95] op_sel_hi:[0,1,1]
	v_pk_fma_f32 v[134:135], v[138:139], v[108:109], v[134:135] op_sel_hi:[0,1,1]
	v_add_f32_dpp v50, v50, v50 row_ror:8 row_mask:0xf bank_mask:0xf bound_ctrl:1
	v_cndmask_b32_e64 v45, v92, v48, s[42:43]
	v_cndmask_b32_e64 v48, v48, v92, s[42:43]
	v_lshlrev_b32_e32 v78, 16, v10
	v_and_b32_e32 v79, 0xffff0000, v10
	v_lshlrev_b32_e32 v80, 16, v11
	v_and_b32_e32 v81, 0xffff0000, v11
	v_add_f32_dpp v50, v50, v50 row_ror:4 row_mask:0xf bank_mask:0xf bound_ctrl:1
	v_lshlrev_b32_e32 v86, 16, v12
	v_and_b32_e32 v87, 0xffff0000, v12
	v_lshlrev_b32_e32 v88, 16, v13
	v_and_b32_e32 v89, 0xffff0000, v13
	v_lshlrev_b32_e32 v102, 16, v2
	v_and_b32_e32 v103, 0xffff0000, v2
	v_add_f32_dpp v50, v50, v50 row_ror:2 row_mask:0xf bank_mask:0xf bound_ctrl:1
	v_add_f32_dpp v45, v48, v45 row_mirror row_mask:0xf bank_mask:0xf bound_ctrl:1
	v_lshlrev_b32_e32 v104, 16, v3
	v_and_b32_e32 v105, 0xffff0000, v3
	v_lshlrev_b32_e32 v118, 16, v4
	v_and_b32_e32 v119, 0xffff0000, v4
	v_lshlrev_b32_e32 v120, 16, v5
	v_and_b32_e32 v121, 0xffff0000, v5
	v_add_f32_dpp v50, v50, v50 row_ror:1 row_mask:0xf bank_mask:0xf bound_ctrl:1
	v_pk_fma_f32 v[14:15], v[50:51], v[110:111], v[94:95] op_sel_hi:[0,1,1] neg_lo:[1,0,0] neg_hi:[1,0,0]
	v_pk_fma_f32 v[16:17], v[50:51], v[112:113], v[134:135] op_sel_hi:[0,1,1] neg_lo:[1,0,0] neg_hi:[1,0,0]
	v_pk_mul_f32 v[94:95], v[14:15], v[122:123]
	ds_write_b128 v93, v[114:117]
	ds_write_b128 v93, v[126:129] offset:16
	v_pk_fma_f32 v[94:95], v[16:17], v[124:125], v[94:95]
	ds_write_b128 v97, v[78:81]
	v_add_f32_e32 v22, v94, v95
	ds_write_b128 v97, v[86:89] offset:16
	ds_write_b128 v51, v[102:105]
	ds_write_b128 v51, v[118:121] offset:16
	v_cndmask_b32_e64 v48, v22, v49, s[42:43]
	v_cndmask_b32_e64 v22, v49, v22, s[42:43]
	s_nop 1
	v_add_f32_dpp v22, v22, v48 row_mirror row_mask:0xf bank_mask:0xf bound_ctrl:1
	v_cndmask_b32_e64 v48, v25, v19, s[44:45]
	v_cndmask_b32_e64 v19, v19, v25, s[44:45]
	v_cndmask_b32_e64 v25, v43, v21, s[44:45]
	v_cndmask_b32_e64 v21, v21, v43, s[44:45]
	v_add_f32_dpp v19, v19, v48 row_half_mirror row_mask:0xf bank_mask:0xf bound_ctrl:1
	s_nop 0
	v_add_f32_dpp v21, v21, v25 row_half_mirror row_mask:0xf bank_mask:0xf bound_ctrl:1
	v_cndmask_b32_e64 v25, v45, v23, s[44:45]
	v_cndmask_b32_e64 v23, v23, v45, s[44:45]
	s_nop 1
	v_add_f32_dpp v23, v23, v25 row_half_mirror row_mask:0xf bank_mask:0xf bound_ctrl:1
	v_cndmask_b32_e64 v25, v22, v24, s[44:45]
	v_cndmask_b32_e64 v22, v24, v22, s[44:45]
	v_cndmask_b32_e64 v24, v23, v19, s[46:47]
	v_cndmask_b32_e64 v19, v19, v23, s[46:47]
	v_add_f32_dpp v22, v22, v25 row_half_mirror row_mask:0xf bank_mask:0xf bound_ctrl:1
	s_nop 0
	v_add_f32_dpp v23, v19, v24 quad_perm:[2,3,0,1] row_mask:0xf bank_mask:0xf bound_ctrl:1
	v_cndmask_b32_e64 v19, v22, v21, s[46:47]
	v_cndmask_b32_e64 v21, v21, v22, s[46:47]
	s_nop 1
	v_add_f32_dpp v21, v21, v19 quad_perm:[2,3,0,1] row_mask:0xf bank_mask:0xf bound_ctrl:1
	v_cndmask_b32_e64 v19, v21, v23, s[48:49]
	v_cndmask_b32_e64 v22, v23, v21, s[48:49]
	v_mov_b32_e32 v21, v1
	s_nop 1
	v_mov_b32_dpp v21, v22 quad_perm:[1,0,3,2] row_mask:0xf bank_mask:0xf
